# GEMM K-loops of P1 and P3: first iteration peeled so each accumulator's first MFMA takes C=0; the 128-register accumulator zero fill before every unit is gone
# speedup vs baseline: 1.0059x; 1.0059x over previous
; #define PG8_STAGE(bufoff, gbase, voff) do { _Pragma("unroll") for (int _i = 0; _i < 2; ++_i) \
;         __builtin_amdgcn_global_load_lds((const unsigned*)((const char*)(gbase) + (voff)[_i]), (PG8_LAS unsigned*)(lds + (bufoff) + ldsw + _i * 8192), 16, 0, 0); } while (0)
; #define PG8_LDA(dst, b, h) do { _Pragma("unroll") for (int m = 0; m < 4; ++m) _Pragma("unroll") for (int k = 0; k < 2; ++k) dst[m][k] = *(const PG8_LAS bf16x8*)(lds + PG8_SA(b, h) + aoff + m * 2048 + k * 1024); } while (0)
; #define PG8_LDB(dst, b, h) do { _Pragma("unroll") for (int n = 0; n < 2; ++n) _Pragma("unroll") for (int k = 0; k < 2; ++k) dst[n][k] = *(const PG8_LAS bf16x8*)(lds + PG8_SB(b, h) + boff + n * 2048 + k * 1024); } while (0)
; #define PG8_WAIT_V(n) asm volatile("s_waitcnt vmcnt(" #n ")" ::: "memory")
; #define PG8_WAIT_L(n) asm volatile("s_waitcnt lgkmcnt(" #n ")" ::: "memory")
; #define PG8_BAR __builtin_amdgcn_s_barrier()
; #define PG8_SCHED __builtin_amdgcn_sched_barrier(0)
; template <class Epi, class Sched, bool ALIGN_EPI = false, bool SP2 = false>
; __device__ __forceinline__ void gemm_phase(PG8_LAS unsigned char* lds, const Gemm g, const Sched& S, const Epi& E) {
;     ...
;         const bool has_next = S.next(ui + 1, nxt);
;         const char* nA = has_next ? (const char*)g.A + (size_t)nxt.pm * tstep : cA; const char* nB = has_next ? (const char*)g.Bt + (size_t)nxt.pn * tstep : cB;
;         for (int t = 0; t < nt; t += 2) {
;             if constexpr (Epi::HAS_MID) { if (t == nt / 2) E.mid(acc, cur, wr, wc, fr, fq); }
;             const bool last = (t == nt - 2);
;             const char* a1 = cA + (size_t)(t + 1) * kstep;
;             const char* a2 = last ? nA : cA + (size_t)(t + 2) * kstep; const char* b2 = last ? nB : cB + (size_t)(t + 2) * kstep;
;             const char* a3 = a2 + kstep; const char* b3 = b2 + kstep;
;             if (last && has_next) S.a_ready(nxt);
;             if constexpr (SP2) {
;             PG8_LDB(B0, 0, 0); PG8_LDB(B1, 0, 1); PG8_SCHED; PG8_LDA(At, 0, 0); PG8_STAGE(PG8_SA(1, 1), a1 + hstep, voffA);
;             PG8_WAIT_V(8); PG8_WAIT_L(0); PG8_BAR; PG8_MMA(0, 0, At, B0); PG8_MMA(0, 1, At, B1); PG8_BAR; PG8_SCHED;
;             PG8_LDA(At, 0, 1); PG8_STAGE(PG8_SB(0, 0), b2, voffB); PG8_STAGE(PG8_SB(0, 1), b2 + hstep, voffB); PG8_STAGE(PG8_SA(0, 0), a2, voffA);
.LBB0_142:
	s_ashr_i32 s81, s80, 31
	s_lshl_b64 s[84:85], s[80:81], 19
	s_add_u32 s84, s98, s84
	s_addc_u32 s85, s99, s85
	s_and_b64 s[86:87], s[8:9], exec
	s_cselect_b32 s1, s85, s89
	s_cselect_b32 s11, s84, s88
	s_ashr_i32 s83, s82, 31
	s_lshl_b64 s[86:87], s[82:83], 19
	s_add_u32 s86, s4, s86
	s_addc_u32 s87, s5, s87
	s_and_b64 s[92:93], s[8:9], exec
	s_cselect_b32 s79, s87, s91
	s_cselect_b32 s81, s86, s90
	s_add_u32 s88, s88, 0x40080
	s_addc_u32 s89, s89, 0
	s_add_u32 s83, s90, 0x100
	s_addc_u32 vcc_lo, s91, 0
	s_mov_b32 vcc_hi, -2
	ds_read_b128 v[130:133], v193
	ds_read_b128 v[134:137], v193 offset:1024
	ds_read_b128 v[138:141], v193 offset:2048
	ds_read_b128 v[142:145], v193 offset:3072
	ds_read_b128 v[166:169], v194
	ds_read_b128 v[170:173], v194 offset:1024
	ds_read_b128 v[174:177], v194 offset:2048
	ds_read_b128 v[178:181], v194 offset:3072
	s_add_u32 s90, s88, 0xfffc0080
	s_addc_u32 s91, s89, -1
	s_cmp_eq_u32 vcc_hi, 12
	s_cselect_b32 s93, s1, s91
	s_cselect_b32 s92, s11, s90
	s_cselect_b32 s91, s79, vcc_lo
	s_cselect_b32 s90, s81, s83
	v_lshl_add_u64 v[190:191], s[88:89], 0, v[156:157]
	s_add_i32 m0, s58, 0xc000
	ds_read_b128 v[182:185], v195
	ds_read_b128 v[186:189], v195 offset:1024
	ds_read_b128 v[200:203], v195 offset:2048
	ds_read_b128 v[204:207], v195 offset:3072
	ds_read_b128 v[208:211], v195 offset:4096
	ds_read_b128 v[212:215], v195 offset:5120
	ds_read_b128 v[216:219], v195 offset:6144
	ds_read_b128 v[220:223], v195 offset:7168
	global_load_lds_dwordx4 v[190:191], off
	v_lshl_add_u64 v[190:191], s[88:89], 0, v[158:159]
	s_add_i32 m0, s58, 0xe000
	s_nop 0
	global_load_lds_dwordx4 v[190:191], off
	s_waitcnt vmcnt(8)
	s_waitcnt lgkmcnt(0)
	s_barrier
	s_setprio 1
	s_waitcnt lgkmcnt(0)
	v_mfma_f32_16x16x32_bf16 v[126:129], v[130:133], v[182:185], 0
	v_mfma_f32_16x16x32_bf16 v[122:125], v[138:141], v[182:185], 0
	v_mfma_f32_16x16x32_bf16 v[110:113], v[130:133], v[200:203], 0
	v_mfma_f32_16x16x32_bf16 v[106:109], v[138:141], v[200:203], 0
	v_mfma_f32_16x16x32_bf16 v[94:97], v[130:133], v[208:211], 0
	v_mfma_f32_16x16x32_bf16 v[90:93], v[138:141], v[208:211], 0
	v_mfma_f32_16x16x32_bf16 v[78:81], v[130:133], v[216:219], 0
	v_mfma_f32_16x16x32_bf16 v[74:77], v[138:141], v[216:219], 0
	v_mfma_f32_16x16x32_bf16 v[126:129], v[134:137], v[186:189], v[126:129]
	v_mfma_f32_16x16x32_bf16 v[122:125], v[142:145], v[186:189], v[122:125]
	v_mfma_f32_16x16x32_bf16 v[110:113], v[134:137], v[204:207], v[110:113]
	v_mfma_f32_16x16x32_bf16 v[106:109], v[142:145], v[204:207], v[106:109]
	v_mfma_f32_16x16x32_bf16 v[94:97], v[134:137], v[212:215], v[94:97]
	v_mfma_f32_16x16x32_bf16 v[90:93], v[142:145], v[212:215], v[90:93]
	v_mfma_f32_16x16x32_bf16 v[78:81], v[134:137], v[220:223], v[78:81]
	v_mfma_f32_16x16x32_bf16 v[74:77], v[142:145], v[220:223], v[74:77]
	v_mfma_f32_16x16x32_bf16 v[118:121], v[166:169], v[182:185], 0
	v_mfma_f32_16x16x32_bf16 v[114:117], v[174:177], v[182:185], 0
	v_mfma_f32_16x16x32_bf16 v[102:105], v[166:169], v[200:203], 0
	v_mfma_f32_16x16x32_bf16 v[98:101], v[174:177], v[200:203], 0
	v_mfma_f32_16x16x32_bf16 v[86:89], v[166:169], v[208:211], 0
	v_mfma_f32_16x16x32_bf16 v[82:85], v[174:177], v[208:211], 0
	v_mfma_f32_16x16x32_bf16 v[70:73], v[166:169], v[216:219], 0
	v_mfma_f32_16x16x32_bf16 v[66:69], v[174:177], v[216:219], 0
	v_mfma_f32_16x16x32_bf16 v[118:121], v[170:173], v[186:189], v[118:121]
	v_mfma_f32_16x16x32_bf16 v[114:117], v[178:181], v[186:189], v[114:117]
	v_mfma_f32_16x16x32_bf16 v[102:105], v[170:173], v[204:207], v[102:105]
	v_mfma_f32_16x16x32_bf16 v[98:101], v[178:181], v[204:207], v[98:101]
	v_mfma_f32_16x16x32_bf16 v[86:89], v[170:173], v[212:215], v[86:89]
	v_mfma_f32_16x16x32_bf16 v[82:85], v[178:181], v[212:215], v[82:85]
	v_mfma_f32_16x16x32_bf16 v[70:73], v[170:173], v[220:223], v[70:73]
	v_mfma_f32_16x16x32_bf16 v[66:69], v[178:181], v[220:223], v[66:69]
	s_setprio 0
	s_barrier
	s_add_i32 s94, s7, s97
	v_lshl_add_u64 v[190:191], s[90:91], 0, v[148:149]
	s_mov_b32 m0, s94
	ds_read_b128 v[182:185], v195 offset:16384
	ds_read_b128 v[186:189], v195 offset:17408
	ds_read_b128 v[200:203], v195 offset:18432
	ds_read_b128 v[204:207], v195 offset:19456
	ds_read_b128 v[208:211], v195 offset:20480
	ds_read_b128 v[212:215], v195 offset:21504
	ds_read_b128 v[216:219], v195 offset:22528
	ds_read_b128 v[220:223], v195 offset:23552
	global_load_lds_dwordx4 v[190:191], off
	s_add_i32 m0, s94, 0x2000
	s_add_u32 s94, s90, 0x40000
	v_lshl_add_u64 v[224:225], s[90:91], 0, v[152:153]
	s_addc_u32 s95, s91, 0
	s_add_i32 s18, s64, s97
	global_load_lds_dwordx4 v[224:225], off
	v_lshl_add_u64 v[226:227], s[94:95], 0, v[148:149]
	s_mov_b32 m0, s18
	v_lshl_add_u64 v[228:229], s[92:93], 0, v[150:151]
	global_load_lds_dwordx4 v[226:227], off
	v_lshl_add_u64 v[226:227], s[94:95], 0, v[152:153]
	s_add_i32 m0, s18, 0x2000
	s_nop 0
	global_load_lds_dwordx4 v[226:227], off
	v_lshl_add_u64 v[226:227], s[92:93], 0, v[146:147]
	s_mov_b32 m0, s58
	s_nop 0
	global_load_lds_dwordx4 v[226:227], off
	s_mov_b32 m0, s59
	s_nop 0
	global_load_lds_dwordx4 v[228:229], off
	s_waitcnt vmcnt(8)
	s_waitcnt lgkmcnt(0)
	s_barrier
; #define PG8_STAGE(bufoff, gbase, voff) do { _Pragma("unroll") for (int _i = 0; _i < 2; ++_i) \
;         __builtin_amdgcn_global_load_lds((const unsigned*)((const char*)(gbase) + (voff)[_i]), (PG8_LAS unsigned*)(lds + (bufoff) + ldsw + _i * 8192), 16, 0, 0); } while (0)
; #define PG8_LDA(dst, b, h) do { _Pragma("unroll") for (int m = 0; m < 4; ++m) _Pragma("unroll") for (int k = 0; k < 2; ++k) dst[m][k] = *(const PG8_LAS bf16x8*)(lds + PG8_SA(b, h) + aoff + m * 2048 + k * 1024); } while (0)
; #define PG8_LDB(dst, b, h) do { _Pragma("unroll") for (int n = 0; n < 2; ++n) _Pragma("unroll") for (int k = 0; k < 2; ++k) dst[n][k] = *(const PG8_LAS bf16x8*)(lds + PG8_SB(b, h) + boff + n * 2048 + k * 1024); } while (0)
; #define PG8_MMA(ai, bj, At, Bt) do { __builtin_amdgcn_s_setprio(1); _Pragma("unroll") for (int m = 0; m < 4; ++m) _Pragma("unroll") for (int n = 0; n < 2; ++n) _Pragma("unroll") for (int k = 0; k < 2; ++k) \
;         acc[ai][bj][m][n] = __builtin_amdgcn_mfma_f32_16x16x32_bf16(Bt[n][k], At[m][k], acc[ai][bj][m][n], 0, 0, 0); __builtin_amdgcn_s_setprio(0); } while (0)
; #define PG8_WAIT_V(n) asm volatile("s_waitcnt vmcnt(" #n ")" ::: "memory")
; #define PG8_WAIT_L(n) asm volatile("s_waitcnt lgkmcnt(" #n ")" ::: "memory")
; #define PG8_BAR __builtin_amdgcn_s_barrier()
; #define PG8_SCHED __builtin_amdgcn_sched_barrier(0)
; template <class Epi, class Sched, bool ALIGN_EPI = false, bool SP2 = false>
; __device__ __forceinline__ void gemm_phase(PG8_LAS unsigned char* lds, const Gemm g, const Sched& S, const Epi& E) {
;     ...
;             PG8_LDA(At, 0, 1); PG8_STAGE(PG8_SB(0, 0), b2, voffB); PG8_STAGE(PG8_SB(0, 1), b2 + hstep, voffB); PG8_STAGE(PG8_SA(0, 0), a2, voffA);
;             PG8_WAIT_V(8); PG8_WAIT_L(0); PG8_BAR; PG8_MMA(1, 0, At, B0); PG8_MMA(1, 1, At, B1); PG8_BAR; PG8_SCHED;
;             PG8_LDB(B0, 1, 0); PG8_LDB(B1, 1, 1); PG8_SCHED; PG8_LDA(At, 1, 0); PG8_STAGE(PG8_SA(0, 1), a2 + hstep, voffA);
;             PG8_WAIT_V(8); PG8_WAIT_L(0); PG8_BAR; PG8_MMA(0, 0, At, B0); PG8_MMA(0, 1, At, B1); PG8_BAR; PG8_SCHED;
	s_setprio 1
	s_waitcnt lgkmcnt(0)
	v_mfma_f32_16x16x32_bf16 v[62:65], v[130:133], v[182:185], 0
	v_mfma_f32_16x16x32_bf16 v[58:61], v[138:141], v[182:185], 0
	v_mfma_f32_16x16x32_bf16 v[46:49], v[130:133], v[200:203], 0
	v_mfma_f32_16x16x32_bf16 v[42:45], v[138:141], v[200:203], 0
	v_mfma_f32_16x16x32_bf16 v[30:33], v[130:133], v[208:211], 0
	v_mfma_f32_16x16x32_bf16 v[26:29], v[138:141], v[208:211], 0
	v_mfma_f32_16x16x32_bf16 v[14:17], v[130:133], v[216:219], 0
	v_mfma_f32_16x16x32_bf16 v[10:13], v[138:141], v[216:219], 0
	v_mfma_f32_16x16x32_bf16 v[62:65], v[134:137], v[186:189], v[62:65]
	v_mfma_f32_16x16x32_bf16 v[58:61], v[142:145], v[186:189], v[58:61]
	v_mfma_f32_16x16x32_bf16 v[46:49], v[134:137], v[204:207], v[46:49]
	v_mfma_f32_16x16x32_bf16 v[42:45], v[142:145], v[204:207], v[42:45]
	v_mfma_f32_16x16x32_bf16 v[30:33], v[134:137], v[212:215], v[30:33]
	v_mfma_f32_16x16x32_bf16 v[26:29], v[142:145], v[212:215], v[26:29]
	v_mfma_f32_16x16x32_bf16 v[14:17], v[134:137], v[220:223], v[14:17]
	v_mfma_f32_16x16x32_bf16 v[10:13], v[142:145], v[220:223], v[10:13]
	v_mfma_f32_16x16x32_bf16 v[54:57], v[166:169], v[182:185], 0
	v_mfma_f32_16x16x32_bf16 v[50:53], v[174:177], v[182:185], 0
	v_mfma_f32_16x16x32_bf16 v[38:41], v[166:169], v[200:203], 0
	v_mfma_f32_16x16x32_bf16 v[34:37], v[174:177], v[200:203], 0
	v_mfma_f32_16x16x32_bf16 v[22:25], v[166:169], v[208:211], 0
	v_mfma_f32_16x16x32_bf16 v[18:21], v[174:177], v[208:211], 0
	v_mfma_f32_16x16x32_bf16 v[6:9], v[166:169], v[216:219], 0
	v_mfma_f32_16x16x32_bf16 v[2:5], v[174:177], v[216:219], 0
	v_mfma_f32_16x16x32_bf16 v[54:57], v[170:173], v[186:189], v[54:57]
	v_mfma_f32_16x16x32_bf16 v[50:53], v[178:181], v[186:189], v[50:53]
	v_mfma_f32_16x16x32_bf16 v[38:41], v[170:173], v[204:207], v[38:41]
	v_mfma_f32_16x16x32_bf16 v[34:37], v[178:181], v[204:207], v[34:37]
	v_mfma_f32_16x16x32_bf16 v[22:25], v[170:173], v[212:215], v[22:25]
	v_mfma_f32_16x16x32_bf16 v[18:21], v[178:181], v[212:215], v[18:21]
	v_mfma_f32_16x16x32_bf16 v[6:9], v[170:173], v[220:223], v[6:9]
	v_mfma_f32_16x16x32_bf16 v[2:5], v[178:181], v[220:223], v[2:5]
	s_setprio 0
	s_barrier
	s_add_i32 s18, 0, 0x18000
	s_add_i32 s94, 0, 0x1c000
	v_add_u32_e32 v142, s18, v192
	v_add_u32_e32 v154, s94, v192
	ds_read_b128 v[130:133], v142
	ds_read_b128 v[134:137], v142 offset:1024
	ds_read_b128 v[138:141], v142 offset:2048
	ds_read_b128 v[142:145], v142 offset:3072
	ds_read_b128 v[166:169], v154
	ds_read_b128 v[170:173], v154 offset:1024
	ds_read_b128 v[174:177], v154 offset:2048
	ds_read_b128 v[178:181], v154 offset:3072
	s_add_u32 s92, s92, 0x40000
	s_addc_u32 s93, s93, 0
	s_mov_b32 m0, s56
	v_lshl_add_u64 v[230:231], s[92:93], 0, v[146:147]
	ds_read_b128 v[182:185], v195 offset:32768
	ds_read_b128 v[186:189], v195 offset:33792
	ds_read_b128 v[200:203], v195 offset:34816
	ds_read_b128 v[204:207], v195 offset:35840
	ds_read_b128 v[208:211], v195 offset:36864
	ds_read_b128 v[212:215], v195 offset:37888
	ds_read_b128 v[216:219], v195 offset:38912
	ds_read_b128 v[220:223], v195 offset:39936
	global_load_lds_dwordx4 v[230:231], off
	v_lshl_add_u64 v[230:231], s[92:93], 0, v[150:151]
	s_mov_b32 m0, s57
	s_nop 0
	global_load_lds_dwordx4 v[230:231], off
	s_waitcnt vmcnt(8)
	s_waitcnt lgkmcnt(0)
	s_barrier
	s_setprio 1
	s_waitcnt lgkmcnt(0)
	v_mfma_f32_16x16x32_bf16 v[126:129], v[130:133], v[182:185], v[126:129]
	v_mfma_f32_16x16x32_bf16 v[122:125], v[138:141], v[182:185], v[122:125]
	v_mfma_f32_16x16x32_bf16 v[110:113], v[130:133], v[200:203], v[110:113]
	v_mfma_f32_16x16x32_bf16 v[106:109], v[138:141], v[200:203], v[106:109]
	v_mfma_f32_16x16x32_bf16 v[94:97], v[130:133], v[208:211], v[94:97]
	v_mfma_f32_16x16x32_bf16 v[90:93], v[138:141], v[208:211], v[90:93]
	v_mfma_f32_16x16x32_bf16 v[78:81], v[130:133], v[216:219], v[78:81]
	v_mfma_f32_16x16x32_bf16 v[74:77], v[138:141], v[216:219], v[74:77]
	v_mfma_f32_16x16x32_bf16 v[126:129], v[134:137], v[186:189], v[126:129]
	v_mfma_f32_16x16x32_bf16 v[122:125], v[142:145], v[186:189], v[122:125]
	v_mfma_f32_16x16x32_bf16 v[110:113], v[134:137], v[204:207], v[110:113]
	v_mfma_f32_16x16x32_bf16 v[106:109], v[142:145], v[204:207], v[106:109]
	v_mfma_f32_16x16x32_bf16 v[94:97], v[134:137], v[212:215], v[94:97]
	v_mfma_f32_16x16x32_bf16 v[90:93], v[142:145], v[212:215], v[90:93]
	v_mfma_f32_16x16x32_bf16 v[78:81], v[134:137], v[220:223], v[78:81]
	v_mfma_f32_16x16x32_bf16 v[74:77], v[142:145], v[220:223], v[74:77]
	v_mfma_f32_16x16x32_bf16 v[118:121], v[166:169], v[182:185], v[118:121]
	v_mfma_f32_16x16x32_bf16 v[114:117], v[174:177], v[182:185], v[114:117]
	v_mfma_f32_16x16x32_bf16 v[102:105], v[166:169], v[200:203], v[102:105]
	v_mfma_f32_16x16x32_bf16 v[98:101], v[174:177], v[200:203], v[98:101]
	v_mfma_f32_16x16x32_bf16 v[86:89], v[166:169], v[208:211], v[86:89]
	v_mfma_f32_16x16x32_bf16 v[82:85], v[174:177], v[208:211], v[82:85]
	v_mfma_f32_16x16x32_bf16 v[70:73], v[166:169], v[216:219], v[70:73]
	v_mfma_f32_16x16x32_bf16 v[66:69], v[174:177], v[216:219], v[66:69]
	v_mfma_f32_16x16x32_bf16 v[118:121], v[170:173], v[186:189], v[118:121]
	v_mfma_f32_16x16x32_bf16 v[114:117], v[178:181], v[186:189], v[114:117]
	v_mfma_f32_16x16x32_bf16 v[102:105], v[170:173], v[204:207], v[102:105]
	v_mfma_f32_16x16x32_bf16 v[98:101], v[178:181], v[204:207], v[98:101]
	v_mfma_f32_16x16x32_bf16 v[86:89], v[170:173], v[212:215], v[86:89]
	v_mfma_f32_16x16x32_bf16 v[82:85], v[178:181], v[212:215], v[82:85]
	v_mfma_f32_16x16x32_bf16 v[70:73], v[170:173], v[220:223], v[70:73]
	v_mfma_f32_16x16x32_bf16 v[66:69], v[178:181], v[220:223], v[66:69]
	s_setprio 0
	s_barrier
; #define PG8_STAGE(bufoff, gbase, voff) do { _Pragma("unroll") for (int _i = 0; _i < 2; ++_i) \
;         __builtin_amdgcn_global_load_lds((const unsigned*)((const char*)(gbase) + (voff)[_i]), (PG8_LAS unsigned*)(lds + (bufoff) + ldsw + _i * 8192), 16, 0, 0); } while (0)
; #define PG8_LDA(dst, b, h) do { _Pragma("unroll") for (int m = 0; m < 4; ++m) _Pragma("unroll") for (int k = 0; k < 2; ++k) dst[m][k] = *(const PG8_LAS bf16x8*)(lds + PG8_SA(b, h) + aoff + m * 2048 + k * 1024); } while (0)
; #define PG8_MMA(ai, bj, At, Bt) do { __builtin_amdgcn_s_setprio(1); _Pragma("unroll") for (int m = 0; m < 4; ++m) _Pragma("unroll") for (int n = 0; n < 2; ++n) _Pragma("unroll") for (int k = 0; k < 2; ++k) \
;         acc[ai][bj][m][n] = __builtin_amdgcn_mfma_f32_16x16x32_bf16(Bt[n][k], At[m][k], acc[ai][bj][m][n], 0, 0, 0); __builtin_amdgcn_s_setprio(0); } while (0)
; #define PG8_WAIT_V(n) asm volatile("s_waitcnt vmcnt(" #n ")" ::: "memory")
; #define PG8_WAIT_L(n) asm volatile("s_waitcnt lgkmcnt(" #n ")" ::: "memory")
; #define PG8_BAR __builtin_amdgcn_s_barrier()
; #define PG8_SCHED __builtin_amdgcn_sched_barrier(0)
; template <class Epi, class Sched, bool ALIGN_EPI = false, bool SP2 = false>
; __device__ __forceinline__ void gemm_phase(PG8_LAS unsigned char* lds, const Gemm g, const Sched& S, const Epi& E) {
;     ...
;             PG8_LDA(At, 1, 1); PG8_STAGE(PG8_SB(1, 0), b3, voffB); PG8_STAGE(PG8_SB(1, 1), b3 + hstep, voffB); PG8_STAGE(PG8_SA(1, 0), a3, voffA);
;             PG8_WAIT_V(8); PG8_WAIT_L(0); PG8_BAR; PG8_MMA(1, 0, At, B0); PG8_MMA(1, 1, At, B1); PG8_BAR; PG8_SCHED;
	s_add_i32 s18, s18, s97
	v_lshl_add_u64 v[190:191], v[190:191], 0, s[74:75]
	s_mov_b32 m0, s18
	ds_read_b128 v[182:185], v195 offset:49152
	ds_read_b128 v[186:189], v195 offset:50176
	ds_read_b128 v[200:203], v195 offset:51200
	ds_read_b128 v[204:207], v195 offset:52224
	ds_read_b128 v[208:211], v195 offset:53248
	ds_read_b128 v[212:215], v195 offset:54272
	ds_read_b128 v[216:219], v195 offset:55296
	ds_read_b128 v[220:223], v195 offset:56320
	global_load_lds_dwordx4 v[190:191], off
	s_add_i32 m0, s18, 0x2000
	s_add_u32 s90, s90, 0x40080
	v_lshl_add_u64 v[190:191], v[224:225], 0, s[74:75]
	s_addc_u32 s91, s91, 0
	s_add_i32 s18, s94, s97
	global_load_lds_dwordx4 v[190:191], off
	v_lshl_add_u64 v[190:191], s[90:91], 0, v[148:149]
	s_mov_b32 m0, s18
	s_nop 0
	global_load_lds_dwordx4 v[190:191], off
	v_lshl_add_u64 v[190:191], s[90:91], 0, v[152:153]
	s_add_i32 m0, s18, 0x2000
	s_nop 0
	global_load_lds_dwordx4 v[190:191], off
	v_lshl_add_u64 v[190:191], v[226:227], 0, s[74:75]
	s_mov_b32 m0, s19
	s_nop 0
	global_load_lds_dwordx4 v[190:191], off
	v_lshl_add_u64 v[190:191], v[228:229], 0, s[74:75]
	s_mov_b32 m0, s66
	s_nop 0
	global_load_lds_dwordx4 v[190:191], off
	s_waitcnt vmcnt(8)
	s_waitcnt lgkmcnt(0)
	s_barrier
	s_setprio 1
	s_waitcnt lgkmcnt(0)
	v_mfma_f32_16x16x32_bf16 v[62:65], v[130:133], v[182:185], v[62:65]
	v_mfma_f32_16x16x32_bf16 v[58:61], v[138:141], v[182:185], v[58:61]
	v_mfma_f32_16x16x32_bf16 v[46:49], v[130:133], v[200:203], v[46:49]
	v_mfma_f32_16x16x32_bf16 v[42:45], v[138:141], v[200:203], v[42:45]
	v_mfma_f32_16x16x32_bf16 v[30:33], v[130:133], v[208:211], v[30:33]
	v_mfma_f32_16x16x32_bf16 v[26:29], v[138:141], v[208:211], v[26:29]
	v_mfma_f32_16x16x32_bf16 v[14:17], v[130:133], v[216:219], v[14:17]
	v_mfma_f32_16x16x32_bf16 v[10:13], v[138:141], v[216:219], v[10:13]
	v_mfma_f32_16x16x32_bf16 v[62:65], v[134:137], v[186:189], v[62:65]
	v_mfma_f32_16x16x32_bf16 v[58:61], v[142:145], v[186:189], v[58:61]
	v_mfma_f32_16x16x32_bf16 v[46:49], v[134:137], v[204:207], v[46:49]
	v_mfma_f32_16x16x32_bf16 v[42:45], v[142:145], v[204:207], v[42:45]
	v_mfma_f32_16x16x32_bf16 v[30:33], v[134:137], v[212:215], v[30:33]
	v_mfma_f32_16x16x32_bf16 v[26:29], v[142:145], v[212:215], v[26:29]
	v_mfma_f32_16x16x32_bf16 v[14:17], v[134:137], v[220:223], v[14:17]
	v_mfma_f32_16x16x32_bf16 v[10:13], v[142:145], v[220:223], v[10:13]
	v_mfma_f32_16x16x32_bf16 v[54:57], v[166:169], v[182:185], v[54:57]
	v_mfma_f32_16x16x32_bf16 v[50:53], v[174:177], v[182:185], v[50:53]
	v_mfma_f32_16x16x32_bf16 v[38:41], v[166:169], v[200:203], v[38:41]
	v_mfma_f32_16x16x32_bf16 v[34:37], v[174:177], v[200:203], v[34:37]
	v_mfma_f32_16x16x32_bf16 v[22:25], v[166:169], v[208:211], v[22:25]
	v_mfma_f32_16x16x32_bf16 v[18:21], v[174:177], v[208:211], v[18:21]
	v_mfma_f32_16x16x32_bf16 v[6:9], v[166:169], v[216:219], v[6:9]
	v_mfma_f32_16x16x32_bf16 v[2:5], v[174:177], v[216:219], v[2:5]
	v_mfma_f32_16x16x32_bf16 v[54:57], v[170:173], v[186:189], v[54:57]
	v_mfma_f32_16x16x32_bf16 v[50:53], v[178:181], v[186:189], v[50:53]
	v_mfma_f32_16x16x32_bf16 v[38:41], v[170:173], v[204:207], v[38:41]
	v_mfma_f32_16x16x32_bf16 v[34:37], v[178:181], v[204:207], v[34:37]
	v_mfma_f32_16x16x32_bf16 v[22:25], v[170:173], v[212:215], v[22:25]
	v_mfma_f32_16x16x32_bf16 v[18:21], v[178:181], v[212:215], v[18:21]
	v_mfma_f32_16x16x32_bf16 v[6:9], v[170:173], v[220:223], v[6:9]
	v_mfma_f32_16x16x32_bf16 v[2:5], v[178:181], v[220:223], v[2:5]
	s_setprio 0
	s_barrier
	s_add_i32 vcc_hi, vcc_hi, 2
	s_add_u32 s88, s88, 0x100
	s_addc_u32 s89, s89, 0
	s_add_u32 s83, s83, 0x100
	s_addc_u32 vcc_lo, vcc_lo, 0
	s_cmp_gt_u32 vcc_hi, 13

; #define PG8_STAGE(bufoff, gbase, voff) do { _Pragma("unroll") for (int _i = 0; _i < 2; ++_i) \
;         __builtin_amdgcn_global_load_lds((const unsigned*)((const char*)(gbase) + (voff)[_i]), (PG8_LAS unsigned*)(lds + (bufoff) + ldsw + _i * 8192), 16, 0, 0); } while (0)
; #define PG8_LDA(dst, b, h) do { _Pragma("unroll") for (int m = 0; m < 4; ++m) _Pragma("unroll") for (int k = 0; k < 2; ++k) dst[m][k] = *(const PG8_LAS bf16x8*)(lds + PG8_SA(b, h) + aoff + m * 2048 + k * 1024); } while (0)
; #define PG8_LDB(dst, b, h) do { _Pragma("unroll") for (int n = 0; n < 2; ++n) _Pragma("unroll") for (int k = 0; k < 2; ++k) dst[n][k] = *(const PG8_LAS bf16x8*)(lds + PG8_SB(b, h) + boff + n * 2048 + k * 1024); } while (0)
; #define PG8_WAIT_V(n) asm volatile("s_waitcnt vmcnt(" #n ")" ::: "memory")
; #define PG8_WAIT_L(n) asm volatile("s_waitcnt lgkmcnt(" #n ")" ::: "memory")
; #define PG8_BAR __builtin_amdgcn_s_barrier()
; #define PG8_SCHED __builtin_amdgcn_sched_barrier(0)
; template <class Epi, class Sched, bool ALIGN_EPI = false, bool SP2 = false>
; __device__ __forceinline__ void gemm_phase(PG8_LAS unsigned char* lds, const Gemm g, const Sched& S, const Epi& E) {
;     ...
;         const bool has_next = S.next(ui + 1, nxt);
;         const char* nA = has_next ? (const char*)g.A + (size_t)nxt.pm * tstep : cA; const char* nB = has_next ? (const char*)g.Bt + (size_t)nxt.pn * tstep : cB;
;         for (int t = 0; t < nt; t += 2) {
;             if constexpr (Epi::HAS_MID) { if (t == nt / 2) E.mid(acc, cur, wr, wc, fr, fq); }
;             const bool last = (t == nt - 2);
;             const char* a1 = cA + (size_t)(t + 1) * kstep;
;             const char* a2 = last ? nA : cA + (size_t)(t + 2) * kstep; const char* b2 = last ? nB : cB + (size_t)(t + 2) * kstep;
;             const char* a3 = a2 + kstep; const char* b3 = b2 + kstep;
;             if (last && has_next) S.a_ready(nxt);
;             if constexpr (SP2) {
;             PG8_LDB(B0, 0, 0); PG8_LDB(B1, 0, 1); PG8_SCHED; PG8_LDA(At, 0, 0); PG8_STAGE(PG8_SA(1, 1), a1 + hstep, voffA);
;             PG8_WAIT_V(8); PG8_WAIT_L(0); PG8_BAR; PG8_MMA(0, 0, At, B0); PG8_MMA(0, 1, At, B1); PG8_BAR; PG8_SCHED;
;             PG8_LDA(At, 0, 1); PG8_STAGE(PG8_SB(0, 0), b2, voffB); PG8_STAGE(PG8_SB(0, 1), b2 + hstep, voffB); PG8_STAGE(PG8_SA(0, 0), a2, voffA);
.LBB0_586:
	s_mov_b32 s28, s31
	s_ashr_i32 s29, s31, 31
	s_lshl_b64 s[38:39], s[28:29], 19
	s_add_u32 s38, s33, s38
	s_addc_u32 s39, s55, s39
	s_mov_b32 s30, s41
	s_and_b64 s[40:41], s[36:37], exec
	s_cselect_b32 s29, s39, s47
	s_cselect_b32 s90, s38, s46
	s_ashr_i32 s31, s30, 31
	s_lshl_b64 s[40:41], s[30:31], 19
	s_add_u32 s40, s56, s40
	s_addc_u32 s41, s57, s41
	s_and_b64 s[48:49], s[36:37], exec
	s_cselect_b32 s31, s41, s61
	s_cselect_b32 s91, s40, s60
	s_lshl_b32 s48, s44, 8
	s_ashr_i32 s43, s42, 31
	s_ashr_i32 s49, s48, 31
	s_lshl_b64 s[44:45], s[42:43], 19
	s_lshl_b64 s[42:43], s[48:49], 1
	s_add_u32 s2, s76, s42
	s_addc_u32 s49, s77, s43
	s_add_u32 s48, s2, s44
	s_addc_u32 s49, s49, s45
	v_mov_b32_e32 v4, v2
	v_mov_b32_e32 v5, v2
	s_add_u32 s92, s60, 0x100
	v_mov_b32_e32 v3, v2
	v_lshl_add_u64 v[204:205], s[46:47], 0, v[198:199]
	v_lshl_add_u64 v[206:207], s[46:47], 0, v[200:201]
	s_addc_u32 s93, s61, 0
	s_mov_b32 s94, -2
	s_mov_b64 s[60:61], 0
	s_add_u32 s2, s46, s60
	s_addc_u32 s62, s47, s61
	s_add_u32 s2, s2, 0x100
	s_addc_u32 s62, s62, 0
	s_add_u32 s95, s92, s60
	s_addc_u32 s63, s93, s61
	s_add_i32 s96, 0, 0x10000
	v_add_u32_e32 v3, s96, v209
	ds_read_b128 v[134:137], v3
	ds_read_b128 v[138:141], v3 offset:1024
	ds_read_b128 v[142:145], v3 offset:2048
	ds_read_b128 v[146:149], v3 offset:3072
	v_add_u32_e32 v3, s88, v209
	ds_read_b128 v[150:153], v3
	ds_read_b128 v[154:157], v3 offset:1024
	ds_read_b128 v[158:161], v3 offset:2048
	ds_read_b128 v[162:165], v3 offset:3072
	s_cmpk_eq_i32 s60, 0x700
	s_cselect_b32 s65, s29, s62
	s_cselect_b32 s64, s90, s2
	s_cselect_b32 s63, s31, s63
	s_cselect_b32 s62, s91, s95
	v_lshl_add_u64 v[4:5], v[204:205], 0, s[60:61]
	s_add_i32 m0, s59, 0xc000
	ds_read_b128 v[166:169], v210
	ds_read_b128 v[170:173], v210 offset:1024
	ds_read_b128 v[174:177], v210 offset:2048
	ds_read_b128 v[178:181], v210 offset:3072
	ds_read_b128 v[182:185], v210 offset:4096
	ds_read_b128 v[186:189], v210 offset:5120
	ds_read_b128 v[212:215], v210 offset:6144
	ds_read_b128 v[216:219], v210 offset:7168
	global_load_lds_dwordx4 v[4:5], off
	v_lshl_add_u64 v[4:5], v[206:207], 0, s[60:61]
	s_add_i32 m0, s59, 0xe000
	s_nop 0
	global_load_lds_dwordx4 v[4:5], off
	s_waitcnt vmcnt(8)
	s_waitcnt lgkmcnt(0)
	s_barrier
	s_setprio 1
	s_waitcnt lgkmcnt(0)
	v_mfma_f32_16x16x32_bf16 v[130:133], v[134:137], v[166:169], 0
	v_mfma_f32_16x16x32_bf16 v[126:129], v[142:145], v[166:169], 0
	v_mfma_f32_16x16x32_bf16 v[114:117], v[134:137], v[174:177], 0
	v_mfma_f32_16x16x32_bf16 v[110:113], v[142:145], v[174:177], 0
	v_mfma_f32_16x16x32_bf16 v[98:101], v[134:137], v[182:185], 0
	v_mfma_f32_16x16x32_bf16 v[94:97], v[142:145], v[182:185], 0
	v_mfma_f32_16x16x32_bf16 v[82:85], v[134:137], v[212:215], 0
	v_mfma_f32_16x16x32_bf16 v[78:81], v[142:145], v[212:215], 0
	v_mfma_f32_16x16x32_bf16 v[130:133], v[138:141], v[170:173], v[130:133]
	v_mfma_f32_16x16x32_bf16 v[126:129], v[146:149], v[170:173], v[126:129]
	v_mfma_f32_16x16x32_bf16 v[114:117], v[138:141], v[178:181], v[114:117]
	v_mfma_f32_16x16x32_bf16 v[110:113], v[146:149], v[178:181], v[110:113]
	v_mfma_f32_16x16x32_bf16 v[98:101], v[138:141], v[186:189], v[98:101]
	v_mfma_f32_16x16x32_bf16 v[94:97], v[146:149], v[186:189], v[94:97]
	v_mfma_f32_16x16x32_bf16 v[82:85], v[138:141], v[216:219], v[82:85]
	v_mfma_f32_16x16x32_bf16 v[78:81], v[146:149], v[216:219], v[78:81]
	v_mfma_f32_16x16x32_bf16 v[122:125], v[150:153], v[166:169], 0
	v_mfma_f32_16x16x32_bf16 v[118:121], v[158:161], v[166:169], 0
	v_mfma_f32_16x16x32_bf16 v[106:109], v[150:153], v[174:177], 0
	v_mfma_f32_16x16x32_bf16 v[102:105], v[158:161], v[174:177], 0
	v_mfma_f32_16x16x32_bf16 v[90:93], v[150:153], v[182:185], 0
	v_mfma_f32_16x16x32_bf16 v[86:89], v[158:161], v[182:185], 0
	v_mfma_f32_16x16x32_bf16 v[74:77], v[150:153], v[212:215], 0
	v_mfma_f32_16x16x32_bf16 v[70:73], v[158:161], v[212:215], 0
	v_mfma_f32_16x16x32_bf16 v[122:125], v[154:157], v[170:173], v[122:125]
	v_mfma_f32_16x16x32_bf16 v[118:121], v[162:165], v[170:173], v[118:121]
	v_mfma_f32_16x16x32_bf16 v[106:109], v[154:157], v[178:181], v[106:109]
	v_mfma_f32_16x16x32_bf16 v[102:105], v[162:165], v[178:181], v[102:105]
	v_mfma_f32_16x16x32_bf16 v[90:93], v[154:157], v[186:189], v[90:93]
	v_mfma_f32_16x16x32_bf16 v[86:89], v[162:165], v[186:189], v[86:89]
	v_mfma_f32_16x16x32_bf16 v[74:77], v[154:157], v[216:219], v[74:77]
	v_mfma_f32_16x16x32_bf16 v[70:73], v[162:165], v[216:219], v[70:73]
	s_setprio 0
	s_barrier
	s_add_i32 s2, s96, s58
	v_lshl_add_u64 v[220:221], s[62:63], 0, v[192:193]
	s_mov_b32 m0, s2
	ds_read_b128 v[166:169], v210 offset:16384
	ds_read_b128 v[170:173], v210 offset:17408
	ds_read_b128 v[174:177], v210 offset:18432
	ds_read_b128 v[178:181], v210 offset:19456
	ds_read_b128 v[182:185], v210 offset:20480
	ds_read_b128 v[186:189], v210 offset:21504
	ds_read_b128 v[212:215], v210 offset:22528
	ds_read_b128 v[216:219], v210 offset:23552
	global_load_lds_dwordx4 v[220:221], off
	s_add_i32 m0, s2, 0x2000
	s_add_u32 s96, s62, 0x40000
	v_lshl_add_u64 v[222:223], s[62:63], 0, v[196:197]
	s_addc_u32 s97, s63, 0
	s_add_i32 s2, s88, s58
	global_load_lds_dwordx4 v[222:223], off
	v_lshl_add_u64 v[4:5], s[96:97], 0, v[192:193]
	s_mov_b32 m0, s2
	v_lshl_add_u64 v[224:225], s[64:65], 0, v[190:191]
	global_load_lds_dwordx4 v[4:5], off
	v_lshl_add_u64 v[4:5], s[96:97], 0, v[196:197]
	s_add_i32 m0, s2, 0x2000
	v_lshl_add_u64 v[226:227], s[64:65], 0, v[194:195]
	global_load_lds_dwordx4 v[4:5], off
	s_mov_b32 m0, s59
	s_nop 0
	global_load_lds_dwordx4 v[224:225], off
	s_mov_b32 m0, s66
	s_nop 0
	global_load_lds_dwordx4 v[226:227], off
	s_waitcnt vmcnt(8)
	s_waitcnt lgkmcnt(0)
	s_barrier
; #define PG8_STAGE(bufoff, gbase, voff) do { _Pragma("unroll") for (int _i = 0; _i < 2; ++_i) \
;         __builtin_amdgcn_global_load_lds((const unsigned*)((const char*)(gbase) + (voff)[_i]), (PG8_LAS unsigned*)(lds + (bufoff) + ldsw + _i * 8192), 16, 0, 0); } while (0)
; #define PG8_LDA(dst, b, h) do { _Pragma("unroll") for (int m = 0; m < 4; ++m) _Pragma("unroll") for (int k = 0; k < 2; ++k) dst[m][k] = *(const PG8_LAS bf16x8*)(lds + PG8_SA(b, h) + aoff + m * 2048 + k * 1024); } while (0)
; #define PG8_LDB(dst, b, h) do { _Pragma("unroll") for (int n = 0; n < 2; ++n) _Pragma("unroll") for (int k = 0; k < 2; ++k) dst[n][k] = *(const PG8_LAS bf16x8*)(lds + PG8_SB(b, h) + boff + n * 2048 + k * 1024); } while (0)
; #define PG8_MMA(ai, bj, At, Bt) do { __builtin_amdgcn_s_setprio(1); _Pragma("unroll") for (int m = 0; m < 4; ++m) _Pragma("unroll") for (int n = 0; n < 2; ++n) _Pragma("unroll") for (int k = 0; k < 2; ++k) \
;         acc[ai][bj][m][n] = __builtin_amdgcn_mfma_f32_16x16x32_bf16(Bt[n][k], At[m][k], acc[ai][bj][m][n], 0, 0, 0); __builtin_amdgcn_s_setprio(0); } while (0)
; #define PG8_WAIT_V(n) asm volatile("s_waitcnt vmcnt(" #n ")" ::: "memory")
; #define PG8_WAIT_L(n) asm volatile("s_waitcnt lgkmcnt(" #n ")" ::: "memory")
; #define PG8_BAR __builtin_amdgcn_s_barrier()
; #define PG8_SCHED __builtin_amdgcn_sched_barrier(0)
; template <class Epi, class Sched, bool ALIGN_EPI = false, bool SP2 = false>
; __device__ __forceinline__ void gemm_phase(PG8_LAS unsigned char* lds, const Gemm g, const Sched& S, const Epi& E) {
;     ...
;             PG8_LDA(At, 0, 1); PG8_STAGE(PG8_SB(0, 0), b2, voffB); PG8_STAGE(PG8_SB(0, 1), b2 + hstep, voffB); PG8_STAGE(PG8_SA(0, 0), a2, voffA);
;             PG8_WAIT_V(8); PG8_WAIT_L(0); PG8_BAR; PG8_MMA(1, 0, At, B0); PG8_MMA(1, 1, At, B1); PG8_BAR; PG8_SCHED;
;             PG8_LDB(B0, 1, 0); PG8_LDB(B1, 1, 1); PG8_SCHED; PG8_LDA(At, 1, 0); PG8_STAGE(PG8_SA(0, 1), a2 + hstep, voffA);
;             PG8_WAIT_V(8); PG8_WAIT_L(0); PG8_BAR; PG8_MMA(0, 0, At, B0); PG8_MMA(0, 1, At, B1); PG8_BAR; PG8_SCHED;
	s_setprio 1
	s_waitcnt lgkmcnt(0)
	v_mfma_f32_16x16x32_bf16 v[66:69], v[134:137], v[166:169], 0
	v_mfma_f32_16x16x32_bf16 v[62:65], v[142:145], v[166:169], 0
	v_mfma_f32_16x16x32_bf16 v[50:53], v[134:137], v[174:177], 0
	v_mfma_f32_16x16x32_bf16 v[46:49], v[142:145], v[174:177], 0
	v_mfma_f32_16x16x32_bf16 v[34:37], v[134:137], v[182:185], 0
	v_mfma_f32_16x16x32_bf16 v[30:33], v[142:145], v[182:185], 0
	v_mfma_f32_16x16x32_bf16 v[18:21], v[134:137], v[212:215], 0
	v_mfma_f32_16x16x32_bf16 v[14:17], v[142:145], v[212:215], 0
	v_mfma_f32_16x16x32_bf16 v[66:69], v[138:141], v[170:173], v[66:69]
	v_mfma_f32_16x16x32_bf16 v[62:65], v[146:149], v[170:173], v[62:65]
	v_mfma_f32_16x16x32_bf16 v[50:53], v[138:141], v[178:181], v[50:53]
	v_mfma_f32_16x16x32_bf16 v[46:49], v[146:149], v[178:181], v[46:49]
	v_mfma_f32_16x16x32_bf16 v[34:37], v[138:141], v[186:189], v[34:37]
	v_mfma_f32_16x16x32_bf16 v[30:33], v[146:149], v[186:189], v[30:33]
	v_mfma_f32_16x16x32_bf16 v[18:21], v[138:141], v[216:219], v[18:21]
	v_mfma_f32_16x16x32_bf16 v[14:17], v[146:149], v[216:219], v[14:17]
	v_mfma_f32_16x16x32_bf16 v[58:61], v[150:153], v[166:169], 0
	v_mfma_f32_16x16x32_bf16 v[54:57], v[158:161], v[166:169], 0
	v_mfma_f32_16x16x32_bf16 v[42:45], v[150:153], v[174:177], 0
	v_mfma_f32_16x16x32_bf16 v[38:41], v[158:161], v[174:177], 0
	v_mfma_f32_16x16x32_bf16 v[26:29], v[150:153], v[182:185], 0
	v_mfma_f32_16x16x32_bf16 v[22:25], v[158:161], v[182:185], 0
	v_mfma_f32_16x16x32_bf16 v[10:13], v[150:153], v[212:215], 0
	v_mfma_f32_16x16x32_bf16 v[4:7], v[158:161], v[212:215], 0
	v_mfma_f32_16x16x32_bf16 v[58:61], v[154:157], v[170:173], v[58:61]
	v_mfma_f32_16x16x32_bf16 v[54:57], v[162:165], v[170:173], v[54:57]
	v_mfma_f32_16x16x32_bf16 v[42:45], v[154:157], v[178:181], v[42:45]
	v_mfma_f32_16x16x32_bf16 v[38:41], v[162:165], v[178:181], v[38:41]
	v_mfma_f32_16x16x32_bf16 v[26:29], v[154:157], v[186:189], v[26:29]
	v_mfma_f32_16x16x32_bf16 v[22:25], v[162:165], v[186:189], v[22:25]
	v_mfma_f32_16x16x32_bf16 v[10:13], v[154:157], v[216:219], v[10:13]
	v_mfma_f32_16x16x32_bf16 v[4:7], v[162:165], v[216:219], v[4:7]
	s_setprio 0
	s_barrier
	s_add_i32 s2, 0, 0x18000
	v_add_u32_e32 v3, s2, v209
	s_add_i32 s95, 0, 0x1c000
	ds_read_b128 v[134:137], v3
	ds_read_b128 v[138:141], v3 offset:1024
	ds_read_b128 v[142:145], v3 offset:2048
	ds_read_b128 v[146:149], v3 offset:3072
	v_add_u32_e32 v3, s95, v209
	ds_read_b128 v[150:153], v3
	ds_read_b128 v[154:157], v3 offset:1024
	ds_read_b128 v[158:161], v3 offset:2048
	ds_read_b128 v[162:165], v3 offset:3072
	s_add_u32 s64, s64, 0x40000
	s_addc_u32 s65, s65, 0
	s_mov_b32 m0, s67
	v_lshl_add_u64 v[8:9], s[64:65], 0, v[190:191]
	ds_read_b128 v[166:169], v210 offset:32768
	ds_read_b128 v[170:173], v210 offset:33792
	ds_read_b128 v[174:177], v210 offset:34816
	ds_read_b128 v[178:181], v210 offset:35840
	ds_read_b128 v[182:185], v210 offset:36864
	ds_read_b128 v[186:189], v210 offset:37888
	ds_read_b128 v[212:215], v210 offset:38912
	ds_read_b128 v[216:219], v210 offset:39936
	global_load_lds_dwordx4 v[8:9], off
	v_lshl_add_u64 v[8:9], s[64:65], 0, v[194:195]
	s_mov_b32 m0, s68
	s_nop 0
	global_load_lds_dwordx4 v[8:9], off
	s_waitcnt vmcnt(8)
	s_waitcnt lgkmcnt(0)
	s_barrier
	s_setprio 1
	s_waitcnt lgkmcnt(0)
	v_mfma_f32_16x16x32_bf16 v[130:133], v[134:137], v[166:169], v[130:133]
	v_mfma_f32_16x16x32_bf16 v[126:129], v[142:145], v[166:169], v[126:129]
	v_mfma_f32_16x16x32_bf16 v[114:117], v[134:137], v[174:177], v[114:117]
	v_mfma_f32_16x16x32_bf16 v[110:113], v[142:145], v[174:177], v[110:113]
	v_mfma_f32_16x16x32_bf16 v[98:101], v[134:137], v[182:185], v[98:101]
	v_mfma_f32_16x16x32_bf16 v[94:97], v[142:145], v[182:185], v[94:97]
	v_mfma_f32_16x16x32_bf16 v[82:85], v[134:137], v[212:215], v[82:85]
	v_mfma_f32_16x16x32_bf16 v[78:81], v[142:145], v[212:215], v[78:81]
	v_mfma_f32_16x16x32_bf16 v[130:133], v[138:141], v[170:173], v[130:133]
	v_mfma_f32_16x16x32_bf16 v[126:129], v[146:149], v[170:173], v[126:129]
	v_mfma_f32_16x16x32_bf16 v[114:117], v[138:141], v[178:181], v[114:117]
	v_mfma_f32_16x16x32_bf16 v[110:113], v[146:149], v[178:181], v[110:113]
	v_mfma_f32_16x16x32_bf16 v[98:101], v[138:141], v[186:189], v[98:101]
	v_mfma_f32_16x16x32_bf16 v[94:97], v[146:149], v[186:189], v[94:97]
	v_mfma_f32_16x16x32_bf16 v[82:85], v[138:141], v[216:219], v[82:85]
	v_mfma_f32_16x16x32_bf16 v[78:81], v[146:149], v[216:219], v[78:81]
	v_mfma_f32_16x16x32_bf16 v[122:125], v[150:153], v[166:169], v[122:125]
	v_mfma_f32_16x16x32_bf16 v[118:121], v[158:161], v[166:169], v[118:121]
	v_mfma_f32_16x16x32_bf16 v[106:109], v[150:153], v[174:177], v[106:109]
	v_mfma_f32_16x16x32_bf16 v[102:105], v[158:161], v[174:177], v[102:105]
	v_mfma_f32_16x16x32_bf16 v[90:93], v[150:153], v[182:185], v[90:93]
	v_mfma_f32_16x16x32_bf16 v[86:89], v[158:161], v[182:185], v[86:89]
	v_mfma_f32_16x16x32_bf16 v[74:77], v[150:153], v[212:215], v[74:77]
	v_mfma_f32_16x16x32_bf16 v[70:73], v[158:161], v[212:215], v[70:73]
	v_mfma_f32_16x16x32_bf16 v[122:125], v[154:157], v[170:173], v[122:125]
	v_mfma_f32_16x16x32_bf16 v[118:121], v[162:165], v[170:173], v[118:121]
	v_mfma_f32_16x16x32_bf16 v[106:109], v[154:157], v[178:181], v[106:109]
	v_mfma_f32_16x16x32_bf16 v[102:105], v[162:165], v[178:181], v[102:105]
	v_mfma_f32_16x16x32_bf16 v[90:93], v[154:157], v[186:189], v[90:93]
	v_mfma_f32_16x16x32_bf16 v[86:89], v[162:165], v[186:189], v[86:89]
	v_mfma_f32_16x16x32_bf16 v[74:77], v[154:157], v[216:219], v[74:77]
	v_mfma_f32_16x16x32_bf16 v[70:73], v[162:165], v[216:219], v[70:73]
	s_setprio 0
	s_barrier
; #define PG8_STAGE(bufoff, gbase, voff) do { _Pragma("unroll") for (int _i = 0; _i < 2; ++_i) \
;         __builtin_amdgcn_global_load_lds((const unsigned*)((const char*)(gbase) + (voff)[_i]), (PG8_LAS unsigned*)(lds + (bufoff) + ldsw + _i * 8192), 16, 0, 0); } while (0)
; #define PG8_LDA(dst, b, h) do { _Pragma("unroll") for (int m = 0; m < 4; ++m) _Pragma("unroll") for (int k = 0; k < 2; ++k) dst[m][k] = *(const PG8_LAS bf16x8*)(lds + PG8_SA(b, h) + aoff + m * 2048 + k * 1024); } while (0)
; #define PG8_MMA(ai, bj, At, Bt) do { __builtin_amdgcn_s_setprio(1); _Pragma("unroll") for (int m = 0; m < 4; ++m) _Pragma("unroll") for (int n = 0; n < 2; ++n) _Pragma("unroll") for (int k = 0; k < 2; ++k) \
;         acc[ai][bj][m][n] = __builtin_amdgcn_mfma_f32_16x16x32_bf16(Bt[n][k], At[m][k], acc[ai][bj][m][n], 0, 0, 0); __builtin_amdgcn_s_setprio(0); } while (0)
; #define PG8_WAIT_V(n) asm volatile("s_waitcnt vmcnt(" #n ")" ::: "memory")
; #define PG8_WAIT_L(n) asm volatile("s_waitcnt lgkmcnt(" #n ")" ::: "memory")
; #define PG8_BAR __builtin_amdgcn_s_barrier()
; #define PG8_SCHED __builtin_amdgcn_sched_barrier(0)
; template <class Epi, class Sched, bool ALIGN_EPI = false, bool SP2 = false>
; __device__ __forceinline__ void gemm_phase(PG8_LAS unsigned char* lds, const Gemm g, const Sched& S, const Epi& E) {
;     ...
;             PG8_LDA(At, 1, 1); PG8_STAGE(PG8_SB(1, 0), b3, voffB); PG8_STAGE(PG8_SB(1, 1), b3 + hstep, voffB); PG8_STAGE(PG8_SA(1, 0), a3, voffA);
;             PG8_WAIT_V(8); PG8_WAIT_L(0); PG8_BAR; PG8_MMA(1, 0, At, B0); PG8_MMA(1, 1, At, B1); PG8_BAR; PG8_SCHED;
	s_add_i32 s2, s2, s58
	v_lshl_add_u64 v[8:9], v[220:221], 0, s[22:23]
	s_mov_b32 m0, s2
	ds_read_b128 v[166:169], v210 offset:49152
	ds_read_b128 v[170:173], v210 offset:50176
	ds_read_b128 v[174:177], v210 offset:51200
	ds_read_b128 v[178:181], v210 offset:52224
	ds_read_b128 v[182:185], v210 offset:53248
	ds_read_b128 v[186:189], v210 offset:54272
	ds_read_b128 v[212:215], v210 offset:55296
	ds_read_b128 v[216:219], v210 offset:56320
	global_load_lds_dwordx4 v[8:9], off
	s_add_i32 m0, s2, 0x2000
	s_add_u32 s62, s62, 0x40080
	v_lshl_add_u64 v[8:9], v[222:223], 0, s[22:23]
	s_addc_u32 s63, s63, 0
	s_add_i32 s2, s95, s58
	global_load_lds_dwordx4 v[8:9], off
	v_lshl_add_u64 v[8:9], s[62:63], 0, v[192:193]
	s_mov_b32 m0, s2
	s_nop 0
	global_load_lds_dwordx4 v[8:9], off
	v_lshl_add_u64 v[8:9], s[62:63], 0, v[196:197]
	s_add_i32 m0, s2, 0x2000
	s_nop 0
	global_load_lds_dwordx4 v[8:9], off
	v_lshl_add_u64 v[8:9], v[224:225], 0, s[22:23]
	s_mov_b32 m0, s72
	s_nop 0
	global_load_lds_dwordx4 v[8:9], off
	v_lshl_add_u64 v[8:9], v[226:227], 0, s[22:23]
	s_mov_b32 m0, s73
	s_nop 0
	global_load_lds_dwordx4 v[8:9], off
	s_waitcnt vmcnt(8)
	s_waitcnt lgkmcnt(0)
	s_barrier
	s_setprio 1
	s_waitcnt lgkmcnt(0)
	v_mfma_f32_16x16x32_bf16 v[66:69], v[134:137], v[166:169], v[66:69]
	v_mfma_f32_16x16x32_bf16 v[62:65], v[142:145], v[166:169], v[62:65]
	v_mfma_f32_16x16x32_bf16 v[50:53], v[134:137], v[174:177], v[50:53]
	v_mfma_f32_16x16x32_bf16 v[46:49], v[142:145], v[174:177], v[46:49]
	v_mfma_f32_16x16x32_bf16 v[34:37], v[134:137], v[182:185], v[34:37]
	v_mfma_f32_16x16x32_bf16 v[30:33], v[142:145], v[182:185], v[30:33]
	v_mfma_f32_16x16x32_bf16 v[18:21], v[134:137], v[212:215], v[18:21]
	v_mfma_f32_16x16x32_bf16 v[14:17], v[142:145], v[212:215], v[14:17]
	v_mfma_f32_16x16x32_bf16 v[66:69], v[138:141], v[170:173], v[66:69]
	v_mfma_f32_16x16x32_bf16 v[62:65], v[146:149], v[170:173], v[62:65]
	v_mfma_f32_16x16x32_bf16 v[50:53], v[138:141], v[178:181], v[50:53]
	v_mfma_f32_16x16x32_bf16 v[46:49], v[146:149], v[178:181], v[46:49]
	v_mfma_f32_16x16x32_bf16 v[34:37], v[138:141], v[186:189], v[34:37]
	v_mfma_f32_16x16x32_bf16 v[30:33], v[146:149], v[186:189], v[30:33]
	v_mfma_f32_16x16x32_bf16 v[18:21], v[138:141], v[216:219], v[18:21]
	v_mfma_f32_16x16x32_bf16 v[14:17], v[146:149], v[216:219], v[14:17]
	v_mfma_f32_16x16x32_bf16 v[58:61], v[150:153], v[166:169], v[58:61]
	v_mfma_f32_16x16x32_bf16 v[54:57], v[158:161], v[166:169], v[54:57]
	v_mfma_f32_16x16x32_bf16 v[42:45], v[150:153], v[174:177], v[42:45]
	v_mfma_f32_16x16x32_bf16 v[38:41], v[158:161], v[174:177], v[38:41]
	v_mfma_f32_16x16x32_bf16 v[26:29], v[150:153], v[182:185], v[26:29]
	v_mfma_f32_16x16x32_bf16 v[22:25], v[158:161], v[182:185], v[22:25]
	v_mfma_f32_16x16x32_bf16 v[8:11], v[150:153], v[212:215], v[10:13]
	v_mfma_f32_16x16x32_bf16 v[4:7], v[158:161], v[212:215], v[4:7]
	v_mfma_f32_16x16x32_bf16 v[58:61], v[154:157], v[170:173], v[58:61]
	v_mfma_f32_16x16x32_bf16 v[54:57], v[162:165], v[170:173], v[54:57]
	v_mfma_f32_16x16x32_bf16 v[42:45], v[154:157], v[178:181], v[42:45]
	v_mfma_f32_16x16x32_bf16 v[38:41], v[162:165], v[178:181], v[38:41]
	v_mfma_f32_16x16x32_bf16 v[26:29], v[154:157], v[186:189], v[26:29]
	v_mfma_f32_16x16x32_bf16 v[22:25], v[162:165], v[186:189], v[22:25]
	v_mfma_f32_16x16x32_bf16 v[10:13], v[154:157], v[216:219], v[8:11]
	v_mfma_f32_16x16x32_bf16 v[6:9], v[162:165], v[216:219], v[4:7]
	s_setprio 0
	s_barrier
	s_add_i32 s94, s94, 2
	s_add_u32 s60, s60, 0x100
	s_addc_u32 s61, s61, 0
	s_cmp_gt_u32 s94, 13
	s_branch .LBB0_588
